# fused attention bodies: s_setprio 1 over QK bursts and the whole PV stretch
# speedup vs baseline: 1.0084x; 1.0084x over previous
; #define LAS __attribute__((address_space(3)))
; DI float ex2(float x) { return __builtin_amdgcn_exp2f(x); }
; template <int MODE>
; DI void sub_tile(const bf16x8 (&kf)[4], const bf16x8 (&vf)[2][2], const bf16x8 (&qf)[4], f32x16& o0, f32x16& o1, float& l, bool diag, float offs, float fm, const LAS float* fsp, int r, int h) {
;     ...
;         x = qk_tile(kf, qf);
; #pragma unroll
;         for (int g = 0; g < 4; ++g) {
;             const f32x4 fs = *(const LAS f32x4*)(fsp + 16 * (g >> 1) + 8 * h + 4 * (g & 1));
; #pragma unroll
;             for (int e = 0; e < 4; ++e) p[4 * g + e] = ex2(x[4 * g + e] + (fm - fs[e]));
;         }
;     }
;     if (diag) {
; #pragma unroll
;         for (int i = 0; i < 16; ++i) if (kidx(i, h) > r) p[i] = 0.f;
;     }
; #pragma unroll
;     for (int i = 0; i < 16; ++i) l += p[i];
;     pv_tile(o0, o1, vf, p);
; template <int MODE>
; DI void attn_wg2_item(const bf16_t* Qm, const bf16_t* Km, const bf16_t* Vtm, const float* Fb, const float* KMPb, const bf16_t* G, bf16_t* Y, int bh, int qb2, int halfq, int mixer, float Mb, LAS unsigned char* lds, int tid, int wave, int lane) {
;     ...
;                 bf16x8 kf[4], vf[2][2];
; #pragma unroll
;                 for (int sp = 0; sp < 4; ++sp) kf[sp] = *(LAS bf16x8*)(lb + kra + kk * 32 * 144 + sp * 32);
; #pragma unroll
;                 for (int dd = 0; dd < 2; ++dd)
; #pragma unroll
;                     for (int s = 0; s < 2; ++s) vf[dd][s] = *(LAS bf16x8*)(lb + vra + dd * 32 * 144 + kk * 64 + s * 32);
;                 float offA = mb2, offB = mb2;
;                 if (MODE == 2) { offA = ((nb == qblkA) || ((selA >> nb) & 1u)) ? mb2 : NEGI; offB = ((nb == qblkB) || ((selB >> nb) & 1u)) ? mb2 : NEGI; }
;                 const LAS float* fsp = (const LAS float*)(lb + AW_F) + kk * 32;
;                 if (actA) sub_tile<MODE>(kf, vf, qfA, oA0, oA1, lA, tau == qtA, offA, fmA, fsp, r, h);
;                 if (actB) sub_tile<MODE>(kf, vf, qfB, oB0, oB1, lB, tau == qtB, offB, fmB, fsp, r, h);
.LBB0_331:
	s_mul_i32 s5, s85, 0x4900
	s_add_i32 s50, s5, 0
	s_lshl_b32 s5, s64, 1
	s_cmp_lt_i32 s5, s69
	s_cselect_b64 s[66:67], -1, 0
	s_cmp_lt_i32 s5, s84
	s_cselect_b64 s[64:65], -1, 0
	v_add_u32_e32 v0, s50, v192
	v_add_u32_e32 v15, s50, v196
	s_or_b64 s[78:79], s[66:67], s[64:65]
	s_andn2_b64 vcc, exec, s[78:79]
	v_add_u32_e32 v14, v0, v194
	v_add_u32_e32 v0, v15, v194
	s_cbranch_vccnz .LBB0_340
	ds_read_b128 v[144:147], v14 offset:4608
	ds_read_b128 v[148:151], v14 offset:4640
	ds_read_b128 v[152:155], v14 offset:4672
	ds_read_b128 v[156:159], v14 offset:4704
	ds_read_b128 v[140:143], v0 offset:9280
	ds_read_b128 v[136:139], v0 offset:9312
	ds_read_b128 v[132:135], v0 offset:13888
	ds_read_b128 v[128:131], v0 offset:13920
	s_and_b64 s[78:79], s[66:67], s[64:65]
	s_cbranch_scc0 .Lfox_nf1
	s_or_b32 s78, s5, 1
	s_cmp_eq_u32 s78, s69
	s_cbranch_scc1 .Lfox_nf1
	s_cmp_eq_u32 s78, s84
	s_cbranch_scc1 .Lfox_nf1
	v_add_u32_e32 v179, s50, v197
	ds_read_b128 v[200:203], v179 offset:18560
	ds_read_b128 v[204:207], v179 offset:18576
	ds_read_b128 v[208:211], v179 offset:18624
	ds_read_b128 v[212:215], v179 offset:18640
	s_waitcnt lgkmcnt(0)
	v_sub_f32_e32 v80, v188, v200
	v_sub_f32_e32 v81, v188, v201
	v_sub_f32_e32 v82, v188, v202
	v_sub_f32_e32 v83, v188, v203
	v_sub_f32_e32 v84, v188, v204
	v_sub_f32_e32 v85, v188, v205
	v_sub_f32_e32 v86, v188, v206
	v_sub_f32_e32 v87, v188, v207
	v_sub_f32_e32 v88, v188, v208
	v_sub_f32_e32 v89, v188, v209
	v_sub_f32_e32 v90, v188, v210
	v_sub_f32_e32 v91, v188, v211
	v_sub_f32_e32 v92, v188, v212
	v_sub_f32_e32 v93, v188, v213
	v_sub_f32_e32 v94, v188, v214
	v_sub_f32_e32 v95, v188, v215
	s_nop 1
	s_setprio 1
	v_mfma_f32_32x32x16_bf16 v[80:95], v[144:147], v[96:99], v[80:95]
	v_mfma_f32_32x32x16_bf16 v[80:95], v[148:151], v[100:103], v[80:95]
	v_mfma_f32_32x32x16_bf16 v[80:95], v[152:155], v[104:107], v[80:95]
	v_mfma_f32_32x32x16_bf16 v[80:95], v[156:159], v[108:111], v[80:95]
	s_setprio 0
	v_sub_f32_e32 v220, v190, v200
	v_sub_f32_e32 v221, v190, v201
	v_sub_f32_e32 v222, v190, v202
	v_sub_f32_e32 v223, v190, v203
	v_sub_f32_e32 v224, v190, v204
	v_sub_f32_e32 v225, v190, v205
	v_sub_f32_e32 v226, v190, v206
	v_sub_f32_e32 v227, v190, v207
	v_sub_f32_e32 v228, v190, v208
	v_sub_f32_e32 v229, v190, v209
	v_sub_f32_e32 v230, v190, v210
	v_sub_f32_e32 v231, v190, v211
	v_sub_f32_e32 v232, v190, v212
	v_sub_f32_e32 v233, v190, v213
	v_sub_f32_e32 v234, v190, v214
	v_sub_f32_e32 v235, v190, v215
	s_nop 1
	s_setprio 1
	v_mfma_f32_32x32x16_bf16 v[220:235], v[144:147], v[112:115], v[220:235]
	v_mfma_f32_32x32x16_bf16 v[220:235], v[148:151], v[116:119], v[220:235]
	v_mfma_f32_32x32x16_bf16 v[220:235], v[152:155], v[120:123], v[220:235]
	v_mfma_f32_32x32x16_bf16 v[220:235], v[156:159], v[124:127], v[220:235]
	s_setprio 0
	v_exp_f32_e32 v80, v80
	v_exp_f32_e32 v81, v81
	v_exp_f32_e32 v82, v82
	v_exp_f32_e32 v83, v83
	v_exp_f32_e32 v84, v84
	v_exp_f32_e32 v85, v85
	v_exp_f32_e32 v86, v86
	v_exp_f32_e32 v87, v87
	v_exp_f32_e32 v88, v88
	v_exp_f32_e32 v89, v89
	v_exp_f32_e32 v90, v90
	v_exp_f32_e32 v91, v91
	v_exp_f32_e32 v92, v92
	v_exp_f32_e32 v93, v93
	v_exp_f32_e32 v94, v94
	v_exp_f32_e32 v95, v95
	v_exp_f32_e32 v220, v220
	v_add_f32_e32 v198, v80, v198
	v_exp_f32_e32 v221, v221
	v_add_f32_e32 v198, v81, v198
	v_exp_f32_e32 v222, v222
	v_add_f32_e32 v198, v82, v198
	v_exp_f32_e32 v223, v223
	v_add_f32_e32 v198, v83, v198
	v_exp_f32_e32 v224, v224
	v_add_f32_e32 v198, v84, v198
	v_exp_f32_e32 v225, v225
	v_add_f32_e32 v198, v85, v198
	v_exp_f32_e32 v226, v226
	v_add_f32_e32 v198, v86, v198
	v_exp_f32_e32 v227, v227
	v_add_f32_e32 v198, v87, v198
	v_exp_f32_e32 v228, v228
	v_add_f32_e32 v198, v88, v198
	v_exp_f32_e32 v229, v229
	v_add_f32_e32 v198, v89, v198
	v_exp_f32_e32 v230, v230
	v_add_f32_e32 v198, v90, v198
	v_exp_f32_e32 v231, v231
	v_add_f32_e32 v198, v91, v198
	v_exp_f32_e32 v232, v232
	v_add_f32_e32 v198, v92, v198
	v_exp_f32_e32 v233, v233
	v_add_f32_e32 v198, v93, v198
	v_exp_f32_e32 v234, v234
	v_add_f32_e32 v198, v94, v198
	v_exp_f32_e32 v235, v235
	v_add_f32_e32 v198, v95, v198
	v_cvt_pk_bf16_f32 v80, v80, v81
	v_cvt_pk_bf16_f32 v81, v82, v83
	v_cvt_pk_bf16_f32 v82, v84, v85
	v_cvt_pk_bf16_f32 v83, v86, v87
	v_cvt_pk_bf16_f32 v84, v88, v89
	v_cvt_pk_bf16_f32 v85, v90, v91
	v_cvt_pk_bf16_f32 v86, v92, v93
	v_cvt_pk_bf16_f32 v87, v94, v95
	s_setprio 1
	v_mfma_f32_32x32x16_bf16 v[64:79], v[140:143], v[80:83], v[64:79]
	v_add_f32_e32 v175, v220, v175
	v_add_f32_e32 v175, v221, v175
	v_add_f32_e32 v175, v222, v175
	v_add_f32_e32 v175, v223, v175
	v_mfma_f32_32x32x16_bf16 v[48:63], v[132:135], v[80:83], v[48:63]
	v_add_f32_e32 v175, v224, v175
	v_add_f32_e32 v175, v225, v175
	v_add_f32_e32 v175, v226, v175
	v_add_f32_e32 v175, v227, v175
	v_mfma_f32_32x32x16_bf16 v[64:79], v[136:139], v[84:87], v[64:79]
	v_add_f32_e32 v175, v228, v175
	v_add_f32_e32 v175, v229, v175
	v_add_f32_e32 v175, v230, v175
	v_add_f32_e32 v175, v231, v175
	v_mfma_f32_32x32x16_bf16 v[48:63], v[128:131], v[84:87], v[48:63]
	v_add_f32_e32 v175, v232, v175
	v_add_f32_e32 v175, v233, v175
	v_add_f32_e32 v175, v234, v175
	v_add_f32_e32 v175, v235, v175
	v_cvt_pk_bf16_f32 v220, v220, v221
	v_cvt_pk_bf16_f32 v221, v222, v223
	v_cvt_pk_bf16_f32 v222, v224, v225
	v_cvt_pk_bf16_f32 v223, v226, v227
	v_cvt_pk_bf16_f32 v224, v228, v229
	v_cvt_pk_bf16_f32 v225, v230, v231
	v_cvt_pk_bf16_f32 v226, v232, v233
	v_cvt_pk_bf16_f32 v227, v234, v235
	v_mfma_f32_32x32x16_bf16 v[32:47], v[140:143], v[220:223], v[32:47]
	v_mfma_f32_32x32x16_bf16 v[16:31], v[132:135], v[220:223], v[16:31]
	v_mfma_f32_32x32x16_bf16 v[32:47], v[136:139], v[224:227], v[32:47]
	v_mfma_f32_32x32x16_bf16 v[16:31], v[128:131], v[224:227], v[16:31]
	s_setprio 0
	s_branch .LBB0_340

; #define LAS __attribute__((address_space(3)))
; DI float ex2(float x) { return __builtin_amdgcn_exp2f(x); }
; template <int MODE>
; DI void sub_tile(const bf16x8 (&kf)[4], const bf16x8 (&vf)[2][2], const bf16x8 (&qf)[4], f32x16& o0, f32x16& o1, float& l, bool diag, float offs, float fm, const LAS float* fsp, int r, int h) {
;     ...
;         x = qk_tile(kf, qf);
; #pragma unroll
;         for (int g = 0; g < 4; ++g) {
;             const f32x4 fs = *(const LAS f32x4*)(fsp + 16 * (g >> 1) + 8 * h + 4 * (g & 1));
; #pragma unroll
;             for (int e = 0; e < 4; ++e) p[4 * g + e] = ex2(x[4 * g + e] + (fm - fs[e]));
;         }
;     }
;     if (diag) {
; #pragma unroll
;         for (int i = 0; i < 16; ++i) if (kidx(i, h) > r) p[i] = 0.f;
;     }
; #pragma unroll
;     for (int i = 0; i < 16; ++i) l += p[i];
;     pv_tile(o0, o1, vf, p);
; template <int MODE>
; DI void attn_wg2_item(const bf16_t* Qm, const bf16_t* Km, const bf16_t* Vtm, const float* Fb, const float* KMPb, const bf16_t* G, bf16_t* Y, int bh, int qb2, int halfq, int mixer, float Mb, LAS unsigned char* lds, int tid, int wave, int lane) {
;     ...
;                 bf16x8 kf[4], vf[2][2];
; #pragma unroll
;                 for (int sp = 0; sp < 4; ++sp) kf[sp] = *(LAS bf16x8*)(lb + kra + kk * 32 * 144 + sp * 32);
; #pragma unroll
;                 for (int dd = 0; dd < 2; ++dd)
; #pragma unroll
;                     for (int s = 0; s < 2; ++s) vf[dd][s] = *(LAS bf16x8*)(lb + vra + dd * 32 * 144 + kk * 64 + s * 32);
;                 float offA = mb2, offB = mb2;
;                 if (MODE == 2) { offA = ((nb == qblkA) || ((selA >> nb) & 1u)) ? mb2 : NEGI; offB = ((nb == qblkB) || ((selB >> nb) & 1u)) ? mb2 : NEGI; }
;                 const LAS float* fsp = (const LAS float*)(lb + AW_F) + kk * 32;
;                 if (actA) sub_tile<MODE>(kf, vf, qfA, oA0, oA1, lA, tau == qtA, offA, fmA, fsp, r, h);
;                 if (actB) sub_tile<MODE>(kf, vf, qfB, oB0, oB1, lB, tau == qtB, offB, fmB, fsp, r, h);
.LBB0_340:
	s_cmp_le_i32 s5, s69
	s_cselect_b64 s[66:67], -1, 0
	s_cmp_le_i32 s5, s84
	s_cselect_b64 s[64:65], -1, 0
	s_or_b64 s[78:79], s[66:67], s[64:65]
	s_andn2_b64 vcc, exec, s[78:79]
	s_cbranch_vccnz .LBB0_349
	s_waitcnt lgkmcnt(4)
	ds_read_b128 v[156:159], v14
	ds_read_b128 v[144:147], v14 offset:32
	ds_read_b128 v[148:151], v14 offset:64
	ds_read_b128 v[152:155], v14 offset:96
	s_waitcnt lgkmcnt(7)
	ds_read_b128 v[140:143], v0 offset:9216
	s_waitcnt lgkmcnt(7)
	ds_read_b128 v[136:139], v0 offset:9248
	s_waitcnt lgkmcnt(7)
	ds_read_b128 v[132:135], v0 offset:13824
	s_waitcnt lgkmcnt(7)
	ds_read_b128 v[128:131], v0 offset:13856
	s_and_b64 s[78:79], s[66:67], s[64:65]
	s_cbranch_scc0 .Lfox_nf0
	s_cmp_eq_u32 s5, s69
	s_cbranch_scc1 .Lfox_nf0
	s_cmp_eq_u32 s5, s84
	s_cbranch_scc1 .Lfox_nf0
	v_add_u32_e32 v0, s50, v197
	ds_read_b128 v[200:203], v0 offset:18432
	ds_read_b128 v[204:207], v0 offset:18448
	ds_read_b128 v[208:211], v0 offset:18496
	ds_read_b128 v[212:215], v0 offset:18512
	s_waitcnt lgkmcnt(0)
	v_sub_f32_e32 v80, v188, v200
	v_sub_f32_e32 v81, v188, v201
	v_sub_f32_e32 v82, v188, v202
	v_sub_f32_e32 v83, v188, v203
	v_sub_f32_e32 v84, v188, v204
	v_sub_f32_e32 v85, v188, v205
	v_sub_f32_e32 v86, v188, v206
	v_sub_f32_e32 v87, v188, v207
	v_sub_f32_e32 v88, v188, v208
	v_sub_f32_e32 v89, v188, v209
	v_sub_f32_e32 v90, v188, v210
	v_sub_f32_e32 v91, v188, v211
	v_sub_f32_e32 v92, v188, v212
	v_sub_f32_e32 v93, v188, v213
	v_sub_f32_e32 v94, v188, v214
	v_sub_f32_e32 v95, v188, v215
	s_nop 1
	s_setprio 1
	v_mfma_f32_32x32x16_bf16 v[80:95], v[156:159], v[96:99], v[80:95]
	v_mfma_f32_32x32x16_bf16 v[80:95], v[144:147], v[100:103], v[80:95]
	v_mfma_f32_32x32x16_bf16 v[80:95], v[148:151], v[104:107], v[80:95]
	v_mfma_f32_32x32x16_bf16 v[80:95], v[152:155], v[108:111], v[80:95]
	s_setprio 0
	v_sub_f32_e32 v220, v190, v200
	v_sub_f32_e32 v221, v190, v201
	v_sub_f32_e32 v222, v190, v202
	v_sub_f32_e32 v223, v190, v203
	v_sub_f32_e32 v224, v190, v204
	v_sub_f32_e32 v225, v190, v205
	v_sub_f32_e32 v226, v190, v206
	v_sub_f32_e32 v227, v190, v207
	v_sub_f32_e32 v228, v190, v208
	v_sub_f32_e32 v229, v190, v209
	v_sub_f32_e32 v230, v190, v210
	v_sub_f32_e32 v231, v190, v211
	v_sub_f32_e32 v232, v190, v212
	v_sub_f32_e32 v233, v190, v213
	v_sub_f32_e32 v234, v190, v214
	v_sub_f32_e32 v235, v190, v215
	s_nop 1
	s_setprio 1
	v_mfma_f32_32x32x16_bf16 v[220:235], v[156:159], v[112:115], v[220:235]
	v_mfma_f32_32x32x16_bf16 v[220:235], v[144:147], v[116:119], v[220:235]
	v_mfma_f32_32x32x16_bf16 v[220:235], v[148:151], v[120:123], v[220:235]
	v_mfma_f32_32x32x16_bf16 v[220:235], v[152:155], v[124:127], v[220:235]
	s_setprio 0
	v_exp_f32_e32 v80, v80
	v_exp_f32_e32 v81, v81
	v_exp_f32_e32 v82, v82
	v_exp_f32_e32 v83, v83
	v_exp_f32_e32 v84, v84
	v_exp_f32_e32 v85, v85
	v_exp_f32_e32 v86, v86
	v_exp_f32_e32 v87, v87
	v_exp_f32_e32 v88, v88
	v_exp_f32_e32 v89, v89
	v_exp_f32_e32 v90, v90
	v_exp_f32_e32 v91, v91
	v_exp_f32_e32 v92, v92
	v_exp_f32_e32 v93, v93
	v_exp_f32_e32 v94, v94
	v_exp_f32_e32 v95, v95
	v_exp_f32_e32 v220, v220
	v_add_f32_e32 v198, v80, v198
	v_exp_f32_e32 v221, v221
	v_add_f32_e32 v198, v81, v198
	v_exp_f32_e32 v222, v222
	v_add_f32_e32 v198, v82, v198
	v_exp_f32_e32 v223, v223
	v_add_f32_e32 v198, v83, v198
	v_exp_f32_e32 v224, v224
	v_add_f32_e32 v198, v84, v198
	v_exp_f32_e32 v225, v225
	v_add_f32_e32 v198, v85, v198
	v_exp_f32_e32 v226, v226
	v_add_f32_e32 v198, v86, v198
	v_exp_f32_e32 v227, v227
	v_add_f32_e32 v198, v87, v198
	v_exp_f32_e32 v228, v228
	v_add_f32_e32 v198, v88, v198
	v_exp_f32_e32 v229, v229
	v_add_f32_e32 v198, v89, v198
	v_exp_f32_e32 v230, v230
	v_add_f32_e32 v198, v90, v198
	v_exp_f32_e32 v231, v231
	v_add_f32_e32 v198, v91, v198
	v_exp_f32_e32 v232, v232
	v_add_f32_e32 v198, v92, v198
	v_exp_f32_e32 v233, v233
	v_add_f32_e32 v198, v93, v198
	v_exp_f32_e32 v234, v234
	v_add_f32_e32 v198, v94, v198
	v_exp_f32_e32 v235, v235
	v_add_f32_e32 v198, v95, v198
	v_cvt_pk_bf16_f32 v80, v80, v81
	v_cvt_pk_bf16_f32 v81, v82, v83
	v_cvt_pk_bf16_f32 v82, v84, v85
	v_cvt_pk_bf16_f32 v83, v86, v87
	v_cvt_pk_bf16_f32 v84, v88, v89
	v_cvt_pk_bf16_f32 v85, v90, v91
	v_cvt_pk_bf16_f32 v86, v92, v93
	v_cvt_pk_bf16_f32 v87, v94, v95
	s_setprio 1
	v_mfma_f32_32x32x16_bf16 v[64:79], v[140:143], v[80:83], v[64:79]
	v_add_f32_e32 v175, v220, v175
	v_add_f32_e32 v175, v221, v175
	v_add_f32_e32 v175, v222, v175
	v_add_f32_e32 v175, v223, v175
	v_mfma_f32_32x32x16_bf16 v[48:63], v[132:135], v[80:83], v[48:63]
	v_add_f32_e32 v175, v224, v175
	v_add_f32_e32 v175, v225, v175
	v_add_f32_e32 v175, v226, v175
	v_add_f32_e32 v175, v227, v175
	v_mfma_f32_32x32x16_bf16 v[64:79], v[136:139], v[84:87], v[64:79]
	v_add_f32_e32 v175, v228, v175
	v_add_f32_e32 v175, v229, v175
	v_add_f32_e32 v175, v230, v175
	v_add_f32_e32 v175, v231, v175
	v_mfma_f32_32x32x16_bf16 v[48:63], v[128:131], v[84:87], v[48:63]
	v_add_f32_e32 v175, v232, v175
	v_add_f32_e32 v175, v233, v175
	v_add_f32_e32 v175, v234, v175
	v_add_f32_e32 v175, v235, v175
	v_cvt_pk_bf16_f32 v220, v220, v221
	v_cvt_pk_bf16_f32 v221, v222, v223
	v_cvt_pk_bf16_f32 v222, v224, v225
	v_cvt_pk_bf16_f32 v223, v226, v227
	v_cvt_pk_bf16_f32 v224, v228, v229
	v_cvt_pk_bf16_f32 v225, v230, v231
	v_cvt_pk_bf16_f32 v226, v232, v233
	v_cvt_pk_bf16_f32 v227, v234, v235
	v_mfma_f32_32x32x16_bf16 v[32:47], v[140:143], v[220:223], v[32:47]
	v_mfma_f32_32x32x16_bf16 v[16:31], v[132:135], v[220:223], v[16:31]
	v_mfma_f32_32x32x16_bf16 v[32:47], v[136:139], v[224:227], v[32:47]
	v_mfma_f32_32x32x16_bf16 v[16:31], v[128:131], v[224:227], v[16:31]
	s_setprio 0
	s_branch .LBB0_349

; #define LAS __attribute__((address_space(3)))
; DI f32x16 mfma32(bf16x8 a, bf16x8 b, f32x16 c) { return __builtin_amdgcn_mfma_f32_32x32x16_bf16(a, b, c, 0, 0, 0); }
; DI float ex2(float x) { return __builtin_amdgcn_exp2f(x); }
; template <int MODE>
; DI void sub_tile(const bf16x8 (&kf)[4], const bf16x8 (&vf)[2][2], const bf16x8 (&qf)[4], f32x16& o0, f32x16& o1, float& l, bool diag, float offs, float fm, const LAS float* fsp, int r, int h) {
;     ...
;     if (MODE == 2) {
; #pragma unroll
;         for (int i = 0; i < 16; ++i) x[i] = offs;
; #pragma unroll
;         for (int sp = 0; sp < 4; ++sp) x = mfma32(kf[sp], qf[sp], x);
; #pragma unroll
;         for (int i = 0; i < 16; ++i) p[i] = ex2(x[i]);
; template <int MODE>
; DI void attn_wg2_item(const bf16_t* Qm, const bf16_t* Km, const bf16_t* Vtm, const float* Fb, const float* KMPb, const bf16_t* G, bf16_t* Y, int bh, int qb2, int halfq, int mixer, float Mb, LAS unsigned char* lds, int tid, int wave, int lane) {
;     ...
;                 bf16x8 kf[4], vf[2][2];
; #pragma unroll
;                 for (int sp = 0; sp < 4; ++sp) kf[sp] = *(LAS bf16x8*)(lb + kra + kk * 32 * 144 + sp * 32);
; #pragma unroll
;                 for (int dd = 0; dd < 2; ++dd)
; #pragma unroll
;                     for (int s = 0; s < 2; ++s) vf[dd][s] = *(LAS bf16x8*)(lb + vra + dd * 32 * 144 + kk * 64 + s * 32);
;                 float offA = mb2, offB = mb2;
;                 if (MODE == 2) { offA = ((nb == qblkA) || ((selA >> nb) & 1u)) ? mb2 : NEGI; offB = ((nb == qblkB) || ((selB >> nb) & 1u)) ? mb2 : NEGI; }
;                 const LAS float* fsp = (const LAS float*)(lb + AW_F) + kk * 32;
;                 if (actA) sub_tile<MODE>(kf, vf, qfA, oA0, oA1, lA, tau == qtA, offA, fmA, fsp, r, h);
;                 if (actB) sub_tile<MODE>(kf, vf, qfB, oB0, oB1, lB, tau == qtB, offB, fmB, fsp, r, h);
.LBB0_393:
	s_mul_i32 s47, s79, 0x4900
	s_add_i32 s47, s47, 0
	s_lshl_b32 s87, s46, 1
	s_lshr_b32 s88, s46, 2
	s_cmp_lt_i32 s87, s84
	v_add_u32_e32 v0, s47, v175
	v_add_u32_e32 v10, s47, v173
	s_cselect_b64 s[46:47], -1, 0
	s_cmp_lt_i32 s87, s85
	s_cselect_b64 s[64:65], -1, 0
	s_lshl_b32 s89, 1, s88
	v_and_b32_e32 v11, s89, v176
	v_cmp_ne_u32_e32 vcc, 0, v11
	v_and_b32_e32 v11, s89, v177
	s_and_b64 s[48:49], s[46:47], vcc
	v_cmp_ne_u32_e64 s[46:47], 0, v11
	s_and_b64 s[66:67], s[64:65], s[46:47]
	s_or_b64 s[68:69], s[48:49], s[66:67]
	v_add_u32_e32 v14, v0, v172
	v_add_u32_e32 v0, v10, v172
	s_and_saveexec_b64 s[64:65], s[68:69]
	s_cbranch_execz .LBB0_403
	ds_read_b128 v[152:155], v14 offset:4608
	ds_read_b128 v[148:151], v14 offset:4640
	ds_read_b128 v[144:147], v14 offset:4672
	ds_read_b128 v[140:143], v14 offset:4704
	ds_read_b128 v[136:139], v0 offset:9280
	ds_read_b128 v[132:135], v0 offset:9312
	ds_read_b128 v[128:131], v0 offset:13888
	ds_read_b128 v[10:13], v0 offset:13920
	s_or_b32 s90, s87, 1
	s_and_b64 s[92:93], s[48:49], s[66:67]
	s_cbranch_scc0 .Lmoba_nf1
	s_cmp_eq_u32 s90, s84
	s_cbranch_scc1 .Lmoba_nf1
	s_cmp_eq_u32 s90, s85
	s_cbranch_scc1 .Lmoba_nf1
	s_waitcnt lgkmcnt(4)
	s_setprio 1
	v_mfma_f32_32x32x16_bf16 v[80:95], v[152:155], v[96:99], v[196:211]
	v_mfma_f32_32x32x16_bf16 v[80:95], v[148:151], v[100:103], v[80:95]
	v_mfma_f32_32x32x16_bf16 v[80:95], v[144:147], v[104:107], v[80:95]
	v_mfma_f32_32x32x16_bf16 v[80:95], v[140:143], v[108:111], v[80:95]
	v_mfma_f32_32x32x16_bf16 v[228:243], v[152:155], v[112:115], v[212:227]
	v_mfma_f32_32x32x16_bf16 v[228:243], v[148:151], v[116:119], v[228:243]
	v_mfma_f32_32x32x16_bf16 v[228:243], v[144:147], v[120:123], v[228:243]
	v_mfma_f32_32x32x16_bf16 v[228:243], v[140:143], v[124:127], v[228:243]
	s_setprio 0
	s_nop 6
	v_exp_f32_e32 v80, v80
	v_exp_f32_e32 v81, v81
	v_exp_f32_e32 v82, v82
	v_exp_f32_e32 v83, v83
	v_exp_f32_e32 v84, v84
	v_exp_f32_e32 v85, v85
	v_exp_f32_e32 v86, v86
	v_exp_f32_e32 v87, v87
	v_exp_f32_e32 v88, v88
	v_exp_f32_e32 v89, v89
	v_exp_f32_e32 v90, v90
	v_exp_f32_e32 v91, v91
	v_exp_f32_e32 v92, v92
	v_exp_f32_e32 v93, v93
	v_exp_f32_e32 v94, v94
	v_exp_f32_e32 v95, v95
	v_exp_f32_e32 v228, v228
	v_add_f32_e32 v186, v80, v186
	v_exp_f32_e32 v229, v229
	v_add_f32_e32 v186, v81, v186
	v_exp_f32_e32 v230, v230
	v_add_f32_e32 v186, v82, v186
	v_exp_f32_e32 v231, v231
	v_add_f32_e32 v186, v83, v186
	v_exp_f32_e32 v232, v232
	v_add_f32_e32 v186, v84, v186
	v_exp_f32_e32 v233, v233
	v_add_f32_e32 v186, v85, v186
	v_exp_f32_e32 v234, v234
	v_add_f32_e32 v186, v86, v186
	v_exp_f32_e32 v235, v235
	v_add_f32_e32 v186, v87, v186
	v_exp_f32_e32 v236, v236
	v_add_f32_e32 v186, v88, v186
	v_exp_f32_e32 v237, v237
	v_add_f32_e32 v186, v89, v186
	v_exp_f32_e32 v238, v238
	v_add_f32_e32 v186, v90, v186
	v_exp_f32_e32 v239, v239
	v_add_f32_e32 v186, v91, v186
	v_exp_f32_e32 v240, v240
	v_add_f32_e32 v186, v92, v186
	v_exp_f32_e32 v241, v241
	v_add_f32_e32 v186, v93, v186
	v_exp_f32_e32 v242, v242
	v_add_f32_e32 v186, v94, v186
	v_exp_f32_e32 v243, v243
	v_add_f32_e32 v186, v95, v186
	s_waitcnt lgkmcnt(0)
	v_cvt_pk_bf16_f32 v80, v80, v81
	v_cvt_pk_bf16_f32 v81, v82, v83
	v_cvt_pk_bf16_f32 v82, v84, v85
	v_cvt_pk_bf16_f32 v83, v86, v87
	v_cvt_pk_bf16_f32 v84, v88, v89
	v_cvt_pk_bf16_f32 v85, v90, v91
	v_cvt_pk_bf16_f32 v86, v92, v93
	v_cvt_pk_bf16_f32 v87, v94, v95
	s_setprio 1
	v_mfma_f32_32x32x16_bf16 v[64:79], v[136:139], v[80:83], v[64:79]
	v_add_f32_e32 v170, v228, v170
	v_add_f32_e32 v170, v229, v170
	v_add_f32_e32 v170, v230, v170
	v_add_f32_e32 v170, v231, v170
	v_mfma_f32_32x32x16_bf16 v[48:63], v[128:131], v[80:83], v[48:63]
	v_add_f32_e32 v170, v232, v170
	v_add_f32_e32 v170, v233, v170
	v_add_f32_e32 v170, v234, v170
	v_add_f32_e32 v170, v235, v170
	v_mfma_f32_32x32x16_bf16 v[64:79], v[132:135], v[84:87], v[64:79]
	v_add_f32_e32 v170, v236, v170
	v_add_f32_e32 v170, v237, v170
	v_add_f32_e32 v170, v238, v170
	v_add_f32_e32 v170, v239, v170
	v_mfma_f32_32x32x16_bf16 v[48:63], v[10:13], v[84:87], v[48:63]
	v_add_f32_e32 v170, v240, v170
	v_add_f32_e32 v170, v241, v170
	v_add_f32_e32 v170, v242, v170
	v_add_f32_e32 v170, v243, v170
	v_cvt_pk_bf16_f32 v228, v228, v229
	v_cvt_pk_bf16_f32 v229, v230, v231
	v_cvt_pk_bf16_f32 v230, v232, v233
	v_cvt_pk_bf16_f32 v231, v234, v235
	v_cvt_pk_bf16_f32 v232, v236, v237
	v_cvt_pk_bf16_f32 v233, v238, v239
	v_cvt_pk_bf16_f32 v234, v240, v241
	v_cvt_pk_bf16_f32 v235, v242, v243
	v_mfma_f32_32x32x16_bf16 v[32:47], v[136:139], v[228:231], v[32:47]
	v_mfma_f32_32x32x16_bf16 v[16:31], v[128:131], v[228:231], v[16:31]
	v_mfma_f32_32x32x16_bf16 v[32:47], v[132:135], v[232:235], v[32:47]
	v_mfma_f32_32x32x16_bf16 v[16:31], v[10:13], v[232:235], v[16:31]
	s_setprio 0
	s_branch .LBB0_403

; #define LAS __attribute__((address_space(3)))
; DI f32x16 mfma32(bf16x8 a, bf16x8 b, f32x16 c) { return __builtin_amdgcn_mfma_f32_32x32x16_bf16(a, b, c, 0, 0, 0); }
; DI float ex2(float x) { return __builtin_amdgcn_exp2f(x); }
; template <int MODE>
; DI void sub_tile(const bf16x8 (&kf)[4], const bf16x8 (&vf)[2][2], const bf16x8 (&qf)[4], f32x16& o0, f32x16& o1, float& l, bool diag, float offs, float fm, const LAS float* fsp, int r, int h) {
;     ...
;     if (MODE == 2) {
; #pragma unroll
;         for (int i = 0; i < 16; ++i) x[i] = offs;
; #pragma unroll
;         for (int sp = 0; sp < 4; ++sp) x = mfma32(kf[sp], qf[sp], x);
; #pragma unroll
;         for (int i = 0; i < 16; ++i) p[i] = ex2(x[i]);
; template <int MODE>
; DI void attn_wg2_item(const bf16_t* Qm, const bf16_t* Km, const bf16_t* Vtm, const float* Fb, const float* KMPb, const bf16_t* G, bf16_t* Y, int bh, int qb2, int halfq, int mixer, float Mb, LAS unsigned char* lds, int tid, int wave, int lane) {
;     ...
;                 bf16x8 kf[4], vf[2][2];
; #pragma unroll
;                 for (int sp = 0; sp < 4; ++sp) kf[sp] = *(LAS bf16x8*)(lb + kra + kk * 32 * 144 + sp * 32);
; #pragma unroll
;                 for (int dd = 0; dd < 2; ++dd)
; #pragma unroll
;                     for (int s = 0; s < 2; ++s) vf[dd][s] = *(LAS bf16x8*)(lb + vra + dd * 32 * 144 + kk * 64 + s * 32);
;                 float offA = mb2, offB = mb2;
;                 if (MODE == 2) { offA = ((nb == qblkA) || ((selA >> nb) & 1u)) ? mb2 : NEGI; offB = ((nb == qblkB) || ((selB >> nb) & 1u)) ? mb2 : NEGI; }
;                 const LAS float* fsp = (const LAS float*)(lb + AW_F) + kk * 32;
;                 if (actA) sub_tile<MODE>(kf, vf, qfA, oA0, oA1, lA, tau == qtA, offA, fmA, fsp, r, h);
;                 if (actB) sub_tile<MODE>(kf, vf, qfB, oB0, oB1, lB, tau == qtB, offB, fmB, fsp, r, h);
.LBB0_403:
	s_or_b64 exec, exec, s[64:65]
	s_cmp_le_i32 s87, s84
	s_cselect_b64 s[48:49], -1, 0
	s_cmp_le_i32 s87, s85
	s_cselect_b64 s[64:65], -1, 0
	s_and_b64 s[66:67], s[48:49], vcc
	s_and_b64 s[48:49], s[64:65], s[46:47]
	s_or_b64 s[64:65], s[66:67], s[48:49]
	s_and_saveexec_b64 s[46:47], s[64:65]
	s_cbranch_execz .LBB0_413
	s_waitcnt lgkmcnt(7)
	ds_read_b128 v[152:155], v14
	s_waitcnt lgkmcnt(7)
	ds_read_b128 v[148:151], v14 offset:32
	s_waitcnt lgkmcnt(7)
	ds_read_b128 v[144:147], v14 offset:64
	s_waitcnt lgkmcnt(7)
	ds_read_b128 v[140:143], v14 offset:96
	s_waitcnt lgkmcnt(7)
	ds_read_b128 v[136:139], v0 offset:9216
	s_waitcnt lgkmcnt(7)
	ds_read_b128 v[132:135], v0 offset:9248
	s_waitcnt lgkmcnt(7)
	ds_read_b128 v[128:131], v0 offset:13824
	s_waitcnt lgkmcnt(7)
	ds_read_b128 v[10:13], v0 offset:13856
	s_and_b64 s[92:93], s[48:49], s[66:67]
	s_cbranch_scc0 .Lmoba_nf0
	s_cmp_eq_u32 s87, s84
	s_cbranch_scc1 .Lmoba_nf0
	s_cmp_eq_u32 s87, s85
	s_cbranch_scc1 .Lmoba_nf0
	s_waitcnt lgkmcnt(4)
	s_setprio 1
	v_mfma_f32_32x32x16_bf16 v[80:95], v[152:155], v[96:99], v[196:211]
	v_mfma_f32_32x32x16_bf16 v[80:95], v[148:151], v[100:103], v[80:95]
	v_mfma_f32_32x32x16_bf16 v[80:95], v[144:147], v[104:107], v[80:95]
	v_mfma_f32_32x32x16_bf16 v[80:95], v[140:143], v[108:111], v[80:95]
	v_mfma_f32_32x32x16_bf16 v[228:243], v[152:155], v[112:115], v[212:227]
	v_mfma_f32_32x32x16_bf16 v[228:243], v[148:151], v[116:119], v[228:243]
	v_mfma_f32_32x32x16_bf16 v[228:243], v[144:147], v[120:123], v[228:243]
	v_mfma_f32_32x32x16_bf16 v[228:243], v[140:143], v[124:127], v[228:243]
	s_setprio 0
	s_nop 6
	v_exp_f32_e32 v80, v80
	v_exp_f32_e32 v81, v81
	v_exp_f32_e32 v82, v82
	v_exp_f32_e32 v83, v83
	v_exp_f32_e32 v84, v84
	v_exp_f32_e32 v85, v85
	v_exp_f32_e32 v86, v86
	v_exp_f32_e32 v87, v87
	v_exp_f32_e32 v88, v88
	v_exp_f32_e32 v89, v89
	v_exp_f32_e32 v90, v90
	v_exp_f32_e32 v91, v91
	v_exp_f32_e32 v92, v92
	v_exp_f32_e32 v93, v93
	v_exp_f32_e32 v94, v94
	v_exp_f32_e32 v95, v95
	v_exp_f32_e32 v228, v228
	v_add_f32_e32 v186, v80, v186
	v_exp_f32_e32 v229, v229
	v_add_f32_e32 v186, v81, v186
	v_exp_f32_e32 v230, v230
	v_add_f32_e32 v186, v82, v186
	v_exp_f32_e32 v231, v231
	v_add_f32_e32 v186, v83, v186
	v_exp_f32_e32 v232, v232
	v_add_f32_e32 v186, v84, v186
	v_exp_f32_e32 v233, v233
	v_add_f32_e32 v186, v85, v186
	v_exp_f32_e32 v234, v234
	v_add_f32_e32 v186, v86, v186
	v_exp_f32_e32 v235, v235
	v_add_f32_e32 v186, v87, v186
	v_exp_f32_e32 v236, v236
	v_add_f32_e32 v186, v88, v186
	v_exp_f32_e32 v237, v237
	v_add_f32_e32 v186, v89, v186
	v_exp_f32_e32 v238, v238
	v_add_f32_e32 v186, v90, v186
	v_exp_f32_e32 v239, v239
	v_add_f32_e32 v186, v91, v186
	v_exp_f32_e32 v240, v240
	v_add_f32_e32 v186, v92, v186
	v_exp_f32_e32 v241, v241
	v_add_f32_e32 v186, v93, v186
	v_exp_f32_e32 v242, v242
	v_add_f32_e32 v186, v94, v186
	v_exp_f32_e32 v243, v243
	v_add_f32_e32 v186, v95, v186
	s_waitcnt lgkmcnt(0)
	v_cvt_pk_bf16_f32 v80, v80, v81
	v_cvt_pk_bf16_f32 v81, v82, v83
	v_cvt_pk_bf16_f32 v82, v84, v85
	v_cvt_pk_bf16_f32 v83, v86, v87
	v_cvt_pk_bf16_f32 v84, v88, v89
	v_cvt_pk_bf16_f32 v85, v90, v91
	v_cvt_pk_bf16_f32 v86, v92, v93
	v_cvt_pk_bf16_f32 v87, v94, v95
	s_setprio 1
	v_mfma_f32_32x32x16_bf16 v[64:79], v[136:139], v[80:83], v[64:79]
	v_add_f32_e32 v170, v228, v170
	v_add_f32_e32 v170, v229, v170
	v_add_f32_e32 v170, v230, v170
	v_add_f32_e32 v170, v231, v170
	v_mfma_f32_32x32x16_bf16 v[48:63], v[128:131], v[80:83], v[48:63]
	v_add_f32_e32 v170, v232, v170
	v_add_f32_e32 v170, v233, v170
	v_add_f32_e32 v170, v234, v170
	v_add_f32_e32 v170, v235, v170
	v_mfma_f32_32x32x16_bf16 v[64:79], v[132:135], v[84:87], v[64:79]
	v_add_f32_e32 v170, v236, v170
	v_add_f32_e32 v170, v237, v170
	v_add_f32_e32 v170, v238, v170
	v_add_f32_e32 v170, v239, v170
	v_mfma_f32_32x32x16_bf16 v[48:63], v[10:13], v[84:87], v[48:63]
	v_add_f32_e32 v170, v240, v170
	v_add_f32_e32 v170, v241, v170
	v_add_f32_e32 v170, v242, v170
	v_add_f32_e32 v170, v243, v170
	v_cvt_pk_bf16_f32 v228, v228, v229
	v_cvt_pk_bf16_f32 v229, v230, v231
	v_cvt_pk_bf16_f32 v230, v232, v233
	v_cvt_pk_bf16_f32 v231, v234, v235
	v_cvt_pk_bf16_f32 v232, v236, v237
	v_cvt_pk_bf16_f32 v233, v238, v239
	v_cvt_pk_bf16_f32 v234, v240, v241
	v_cvt_pk_bf16_f32 v235, v242, v243
	v_mfma_f32_32x32x16_bf16 v[32:47], v[136:139], v[228:231], v[32:47]
	v_mfma_f32_32x32x16_bf16 v[16:31], v[128:131], v[228:231], v[16:31]
	v_mfma_f32_32x32x16_bf16 v[32:47], v[132:135], v[232:235], v[32:47]
	v_mfma_f32_32x32x16_bf16 v[16:31], v[10:13], v[232:235], v[16:31]
	s_setprio 0
	s_branch .LBB0_413
